# GEMM tile transitions: accumulator clears as v_mov_b64 pairs
# speedup vs baseline: 1.0003x; 1.0003x over previous
.LBB0_156:
	s_ashr_i32 s5, s4, 31
	s_lshl_b64 s[2:3], s[4:5], 19
	s_add_u32 s6, s80, s2
	s_addc_u32 s7, s81, s3
	s_and_b64 s[2:3], s[36:37], exec
	s_cselect_b32 s5, s7, s89
	s_cselect_b32 s92, s6, s88
	s_ashr_i32 s85, s84, 31
	s_lshl_b64 s[2:3], s[84:85], 19
	s_add_u32 s2, s21, s2
	s_addc_u32 s3, s22, s3
	s_and_b64 s[8:9], s[36:37], exec
	s_cselect_b32 s85, s3, s91
	s_cselect_b32 s96, s2, s90
	s_add_u32 vcc_lo, s88, 0x40080
	s_addc_u32 vcc_hi, s89, 0
	s_add_u32 s88, s90, 0x100
	v_mov_b32_e32 v0, 0
	s_addc_u32 s89, s91, 0
	s_mov_b32 s90, -2
	v_mov_b32_e32 v1, 0
	v_mov_b64_e32 v[2:3], 0
	v_mov_b64_e32 v[4:5], 0
	v_mov_b64_e32 v[6:7], 0
	v_mov_b64_e32 v[16:17], 0
	v_mov_b64_e32 v[18:19], 0
	v_mov_b64_e32 v[20:21], 0
	v_mov_b64_e32 v[22:23], 0
	v_mov_b64_e32 v[32:33], 0
	v_mov_b64_e32 v[34:35], 0
	v_mov_b64_e32 v[36:37], 0
	v_mov_b64_e32 v[38:39], 0
	v_mov_b64_e32 v[48:49], 0
	v_mov_b64_e32 v[50:51], 0
	v_mov_b64_e32 v[52:53], 0
	v_mov_b64_e32 v[54:55], 0
	v_mov_b64_e32 v[8:9], 0
	v_mov_b64_e32 v[10:11], 0
	v_mov_b64_e32 v[12:13], 0
	v_mov_b64_e32 v[14:15], 0
	v_mov_b64_e32 v[24:25], 0
	v_mov_b64_e32 v[26:27], 0
	v_mov_b64_e32 v[28:29], 0
	v_mov_b64_e32 v[30:31], 0
	v_mov_b64_e32 v[40:41], 0
	v_mov_b64_e32 v[42:43], 0
	v_mov_b64_e32 v[44:45], 0
	v_mov_b64_e32 v[46:47], 0
	v_mov_b64_e32 v[56:57], 0
	v_mov_b64_e32 v[58:59], 0
	v_mov_b64_e32 v[60:61], 0
	v_mov_b64_e32 v[62:63], 0
	v_mov_b64_e32 v[64:65], 0
	v_mov_b64_e32 v[66:67], 0
	v_mov_b64_e32 v[68:69], 0
	v_mov_b64_e32 v[70:71], 0
	v_mov_b64_e32 v[80:81], 0
	v_mov_b64_e32 v[82:83], 0
	v_mov_b64_e32 v[84:85], 0
	v_mov_b64_e32 v[86:87], 0
	v_mov_b64_e32 v[96:97], 0
	v_mov_b64_e32 v[98:99], 0
	v_mov_b64_e32 v[100:101], 0
	v_mov_b64_e32 v[102:103], 0
	v_mov_b64_e32 v[112:113], 0
	v_mov_b64_e32 v[114:115], 0
	v_mov_b64_e32 v[116:117], 0
	v_mov_b64_e32 v[118:119], 0
	v_mov_b64_e32 v[72:73], 0
	v_mov_b64_e32 v[74:75], 0
	v_mov_b64_e32 v[76:77], 0
	v_mov_b64_e32 v[78:79], 0
	v_mov_b64_e32 v[88:89], 0
	v_mov_b64_e32 v[90:91], 0
	v_mov_b64_e32 v[92:93], 0
	v_mov_b64_e32 v[94:95], 0
	v_mov_b64_e32 v[104:105], 0
	v_mov_b64_e32 v[106:107], 0
	v_mov_b64_e32 v[108:109], 0
	v_mov_b64_e32 v[110:111], 0
	v_mov_b64_e32 v[120:121], 0
	v_mov_b64_e32 v[122:123], 0
	v_mov_b64_e32 v[124:125], 0
	v_mov_b64_e32 v[126:127], 0

.LBB0_437:
	s_ashr_i32 s85, s84, 31
	s_lshl_b64 s[8:9], s[84:85], 19
	s_add_u32 s86, s80, s8
	s_addc_u32 s87, s81, s9
	s_and_b64 s[8:9], s[36:37], exec
	s_cselect_b32 s8, s87, s7
	s_cselect_b32 s9, s86, s6
	s_ashr_i32 s83, s82, 31
	s_lshl_b64 s[88:89], s[82:83], 19
	s_add_u32 s88, s10, s88
	s_addc_u32 s89, s11, s89
	s_and_b64 s[90:91], s[36:37], exec
	s_cselect_b32 s83, s89, s3
	s_cselect_b32 s85, s88, s2
	s_add_u32 s90, s6, 0x40080
	s_addc_u32 s91, s7, 0
	s_add_u32 s92, s2, 0x100
	v_mov_b32_e32 v0, 0
	s_addc_u32 s94, s3, 0
	s_mov_b32 s95, -2
	v_mov_b32_e32 v1, 0
	v_mov_b64_e32 v[2:3], 0
	v_mov_b64_e32 v[4:5], 0
	v_mov_b64_e32 v[6:7], 0
	v_mov_b64_e32 v[8:9], 0
	v_mov_b64_e32 v[10:11], 0
	v_mov_b64_e32 v[12:13], 0
	v_mov_b64_e32 v[14:15], 0
	v_mov_b64_e32 v[24:25], 0
	v_mov_b64_e32 v[26:27], 0
	v_mov_b64_e32 v[28:29], 0
	v_mov_b64_e32 v[30:31], 0
	v_mov_b64_e32 v[40:41], 0
	v_mov_b64_e32 v[42:43], 0
	v_mov_b64_e32 v[44:45], 0
	v_mov_b64_e32 v[46:47], 0
	v_mov_b64_e32 v[16:17], 0
	v_mov_b64_e32 v[18:19], 0
	v_mov_b64_e32 v[20:21], 0
	v_mov_b64_e32 v[22:23], 0
	v_mov_b64_e32 v[32:33], 0
	v_mov_b64_e32 v[34:35], 0
	v_mov_b64_e32 v[36:37], 0
	v_mov_b64_e32 v[38:39], 0
	v_mov_b64_e32 v[48:49], 0
	v_mov_b64_e32 v[50:51], 0
	v_mov_b64_e32 v[52:53], 0
	v_mov_b64_e32 v[54:55], 0
	v_mov_b64_e32 v[56:57], 0
	v_mov_b64_e32 v[58:59], 0
	v_mov_b64_e32 v[60:61], 0
	v_mov_b64_e32 v[62:63], 0
	v_mov_b64_e32 v[64:65], 0
	v_mov_b64_e32 v[66:67], 0
	v_mov_b64_e32 v[68:69], 0
	v_mov_b64_e32 v[70:71], 0
	v_mov_b64_e32 v[72:73], 0
	v_mov_b64_e32 v[74:75], 0
	v_mov_b64_e32 v[76:77], 0
	v_mov_b64_e32 v[78:79], 0
	v_mov_b64_e32 v[88:89], 0
	v_mov_b64_e32 v[90:91], 0
	v_mov_b64_e32 v[92:93], 0
	v_mov_b64_e32 v[94:95], 0
	v_mov_b64_e32 v[104:105], 0
	v_mov_b64_e32 v[106:107], 0
	v_mov_b64_e32 v[108:109], 0
	v_mov_b64_e32 v[110:111], 0
	v_mov_b64_e32 v[80:81], 0
	v_mov_b64_e32 v[82:83], 0
	v_mov_b64_e32 v[84:85], 0
	v_mov_b64_e32 v[86:87], 0
	v_mov_b64_e32 v[96:97], 0
	v_mov_b64_e32 v[98:99], 0
	v_mov_b64_e32 v[100:101], 0
	v_mov_b64_e32 v[102:103], 0
	v_mov_b64_e32 v[112:113], 0
	v_mov_b64_e32 v[114:115], 0
	v_mov_b64_e32 v[116:117], 0
	v_mov_b64_e32 v[118:119], 0
	v_mov_b64_e32 v[120:121], 0
	v_mov_b64_e32 v[122:123], 0
	v_mov_b64_e32 v[124:125], 0
	v_mov_b64_e32 v[126:127], 0

.LBB0_461:
	s_ashr_i32 s85, s84, 31
	s_lshl_b64 s[2:3], s[84:85], 19
	s_add_u32 s86, s10, s2
	s_addc_u32 s87, s11, s3
	s_and_b64 s[2:3], s[82:83], exec
	s_cselect_b32 s72, s87, s91
	s_cselect_b32 s75, s86, s90
	s_ashr_i32 s5, s4, 31
	s_lshl_b64 s[2:3], s[4:5], 19
	s_add_u32 s88, s80, s2
	s_addc_u32 s89, s81, s3
	s_and_b64 s[2:3], s[82:83], exec
	s_cselect_b32 s5, s89, s97
	s_cselect_b32 s85, s88, s96
	s_add_u32 s90, s90, 0x40080
	s_addc_u32 s91, s91, 0
	s_add_u32 s92, s96, 0x100
	v_mov_b32_e32 v0, 0
	s_addc_u32 s94, s97, 0
	s_mov_b32 s95, -2
	v_mov_b32_e32 v1, 0
	v_mov_b64_e32 v[2:3], 0
	v_mov_b64_e32 v[4:5], 0
	v_mov_b64_e32 v[6:7], 0
	v_mov_b64_e32 v[8:9], 0
	v_mov_b64_e32 v[10:11], 0
	v_mov_b64_e32 v[12:13], 0
	v_mov_b64_e32 v[14:15], 0
	v_mov_b64_e32 v[24:25], 0
	v_mov_b64_e32 v[26:27], 0
	v_mov_b64_e32 v[28:29], 0
	v_mov_b64_e32 v[30:31], 0
	v_mov_b64_e32 v[40:41], 0
	v_mov_b64_e32 v[42:43], 0
	v_mov_b64_e32 v[44:45], 0
	v_mov_b64_e32 v[46:47], 0
	v_mov_b64_e32 v[16:17], 0
	v_mov_b64_e32 v[18:19], 0
	v_mov_b64_e32 v[20:21], 0
	v_mov_b64_e32 v[22:23], 0
	v_mov_b64_e32 v[32:33], 0
	v_mov_b64_e32 v[34:35], 0
	v_mov_b64_e32 v[36:37], 0
	v_mov_b64_e32 v[38:39], 0
	v_mov_b64_e32 v[48:49], 0
	v_mov_b64_e32 v[50:51], 0
	v_mov_b64_e32 v[52:53], 0
	v_mov_b64_e32 v[54:55], 0
	v_mov_b64_e32 v[56:57], 0
	v_mov_b64_e32 v[58:59], 0
	v_mov_b64_e32 v[60:61], 0
	v_mov_b64_e32 v[62:63], 0
	v_mov_b64_e32 v[64:65], 0
	v_mov_b64_e32 v[66:67], 0
	v_mov_b64_e32 v[68:69], 0
	v_mov_b64_e32 v[70:71], 0
	v_mov_b64_e32 v[72:73], 0
	v_mov_b64_e32 v[74:75], 0
	v_mov_b64_e32 v[76:77], 0
	v_mov_b64_e32 v[78:79], 0
	v_mov_b64_e32 v[88:89], 0
	v_mov_b64_e32 v[90:91], 0
	v_mov_b64_e32 v[92:93], 0
	v_mov_b64_e32 v[94:95], 0
	v_mov_b64_e32 v[104:105], 0
	v_mov_b64_e32 v[106:107], 0
	v_mov_b64_e32 v[108:109], 0
	v_mov_b64_e32 v[110:111], 0
	v_mov_b64_e32 v[80:81], 0
	v_mov_b64_e32 v[82:83], 0
	v_mov_b64_e32 v[84:85], 0
	v_mov_b64_e32 v[86:87], 0
	v_mov_b64_e32 v[96:97], 0
	v_mov_b64_e32 v[98:99], 0
	v_mov_b64_e32 v[100:101], 0
	v_mov_b64_e32 v[102:103], 0
	v_mov_b64_e32 v[112:113], 0
	v_mov_b64_e32 v[114:115], 0
	v_mov_b64_e32 v[116:117], 0
	v_mov_b64_e32 v[118:119], 0
	v_mov_b64_e32 v[120:121], 0
	v_mov_b64_e32 v[122:123], 0
	v_mov_b64_e32 v[124:125], 0
	v_mov_b64_e32 v[126:127], 0
